# speedup vs baseline: 1.1099x; 1.0004x over previous
; DEV u16 f2bf(float f) { return (u16)(pack2(f, 0.f) & 0xffffu); }
; DEV void phase_win(const Params& P, int l, const u16* __restrict__ xb, const u16* __restrict__ Wt, u16* __restrict__ h, char* smem) {
;     ...
;     if (rope) {
;       const int dst = (cb < 256) ? (C_NQR + cb) : cb;
; #pragma unroll
;       for (int ms = 0; ms < 8; ++ms) {
;       asm volatile("" ::: "memory");
; #pragma unroll
;         for (int j = 0; j < 4; ++j) {
;           int row = m0 + wm * 128 + ms * 16 + quad * 4 + j;
;           int pos = row & (S - 1);
;           u16* hr = h + (size_t)row * HS;
; #pragma unroll
;           for (int ns = 0; ns < 2; ++ns) {
;             int d1 = ns * 16 + l15;
;             float x1 = acc[ms][ns][j], x2 = acc[ms][ns + 2][j];
;             float cs = cosT[pos * 32 + d1], sn = sinT[pos * 32 + d1];
;             hr[dst + d1] = f2bf(x1 * cs - x2 * sn);
;             hr[dst + d1 + 32] = f2bf(x1 * sn + x2 * cs);
;             if (cb < 256) {
;               hr[cb + d1] = f2bf(x1);
;               hr[cb + d1 + 32] = f2bf(x2);
;             }
.LBB0_2077:
	s_or_b64 exec, exec, s[22:23]
	s_and_saveexec_b64 s[12:13], s[4:5]
	s_cbranch_execz .LBB0_2206
	v_add_u32_e32 v0, 0xc80, v130
	v_cndmask_b32_e64 v136, v130, v0, s[10:11]
	v_add_u32_e32 v0, s16, v178
	v_mov_b64_e32 v[132:133], s[72:73]
	s_movk_i32 s4, 0x1b00
	v_lshlrev_b32_e32 v131, 5, v0
	v_mad_i64_i32 v[138:139], s[4:5], v0, s4, v[132:133]
	v_and_b32_e32 v131, 0x1f180, v131
	v_or_b32_e32 v132, v131, v186
	v_add_u32_e32 v160, s16, v178
	v_lshlrev_b32_e32 v160, 5, v160
	v_and_b32_e32 v160, 0x1f180, v160
	v_or_b32_e32 v160, v160, v186
	v_lshlrev_b32_e32 v160, 2, v160
	v_mov_b32_e32 v161, v160
	v_readlane_b32 s4, v252, 58
	v_readlane_b32 s5, v252, 59
	s_nop 4
	global_load_dword v144, v161, s[4:5]
	global_load_dword v145, v161, s[4:5] offset:64
	global_load_dword v146, v161, s[4:5] offset:128
	global_load_dword v147, v161, s[4:5] offset:192
	global_load_dword v148, v161, s[4:5] offset:256
	global_load_dword v149, v161, s[4:5] offset:320
	global_load_dword v150, v161, s[4:5] offset:384
	global_load_dword v151, v161, s[4:5] offset:448
	v_readlane_b32 s4, v252, 60
	v_readlane_b32 s5, v252, 61
	s_nop 4
	global_load_dword v152, v161, s[4:5]
	global_load_dword v153, v161, s[4:5] offset:64
	global_load_dword v154, v161, s[4:5] offset:128
	global_load_dword v155, v161, s[4:5] offset:192
	global_load_dword v156, v161, s[4:5] offset:256
	global_load_dword v157, v161, s[4:5] offset:320
	global_load_dword v158, v161, s[4:5] offset:384
	global_load_dword v159, v161, s[4:5] offset:448
	v_add_u32_e32 v161, 0x800, v160
	v_readlane_b32 s4, v252, 58
	v_readlane_b32 s5, v252, 59
	s_nop 4
	global_load_dword v162, v161, s[4:5]
	global_load_dword v163, v161, s[4:5] offset:64
	global_load_dword v164, v161, s[4:5] offset:128
	global_load_dword v165, v161, s[4:5] offset:192
	global_load_dword v166, v161, s[4:5] offset:256
	global_load_dword v167, v161, s[4:5] offset:320
	global_load_dword v168, v161, s[4:5] offset:384
	global_load_dword v169, v161, s[4:5] offset:448
	v_readlane_b32 s4, v252, 60
	v_readlane_b32 s5, v252, 61
	s_nop 4
	global_load_dword v170, v161, s[4:5]
	global_load_dword v171, v161, s[4:5] offset:64
	global_load_dword v172, v161, s[4:5] offset:128
	global_load_dword v173, v161, s[4:5] offset:192
	global_load_dword v174, v161, s[4:5] offset:256
	global_load_dword v175, v161, s[4:5] offset:320
	global_load_dword v176, v161, s[4:5] offset:384
	global_load_dword v177, v161, s[4:5] offset:448
	s_waitcnt vmcnt(16)
	v_readlane_b32 s4, v252, 58
	v_lshlrev_b32_e32 v132, 2, v132
	v_readlane_b32 s5, v252, 59
	s_nop 4
	v_mov_b32_e32 v137, v144
	v_readlane_b32 s4, v252, 60
	v_readlane_b32 s5, v252, 61
	s_nop 4
	v_mov_b32_e32 v140, v152
	v_mul_f32_e32 v132, v126, v140
	v_fma_f32 v132, v38, v137, -v132
	v_cvt_pk_bf16_f32 v141, v132, s0
	v_or_b32_e32 v132, v136, v186
	v_mul_f32_e32 v140, v38, v140
	v_ashrrev_i32_e32 v133, 31, v132
	v_fmac_f32_e32 v140, v126, v137
	v_lshl_add_u64 v[134:135], v[132:133], 1, v[138:139]
	v_cvt_pk_bf16_f32 v137, v140, s0
	global_store_short v[134:135], v141, off
	global_store_short v[134:135], v137, off offset:64
	v_or_b32_e32 v134, v130, v186
	v_ashrrev_i32_e32 v135, 31, v134
	s_and_saveexec_b64 s[4:5], s[10:11]
	s_cbranch_execz .LBB0_2080
	v_cvt_pk_bf16_f32 v137, v38, s0
	v_lshl_add_u64 v[140:141], v[134:135], 1, v[138:139]
	v_cvt_pk_bf16_f32 v126, v126, s0
	global_store_short v[140:141], v137, off
	global_store_short v[140:141], v126, off offset:64

; DEV u16 f2bf(float f) { return (u16)(pack2(f, 0.f) & 0xffffu); }
; DEV void phase_win(const Params& P, int l, const u16* __restrict__ xb, const u16* __restrict__ Wt, u16* __restrict__ h, char* smem) {
;     ...
;       for (int ms = 0; ms < 8; ++ms) {
;       asm volatile("" ::: "memory");
; #pragma unroll
;         for (int j = 0; j < 4; ++j) {
;           int row = m0 + wm * 128 + ms * 16 + quad * 4 + j;
;           int pos = row & (S - 1);
;           u16* hr = h + (size_t)row * HS;
; #pragma unroll
;           for (int ns = 0; ns < 2; ++ns) {
;             int d1 = ns * 16 + l15;
;             float x1 = acc[ms][ns][j], x2 = acc[ms][ns + 2][j];
;             float cs = cosT[pos * 32 + d1], sn = sinT[pos * 32 + d1];
;             hr[dst + d1] = f2bf(x1 * cs - x2 * sn);
;             hr[dst + d1 + 32] = f2bf(x1 * sn + x2 * cs);
;             if (cb < 256) {
;               hr[cb + d1] = f2bf(x1);
;               hr[cb + d1 + 32] = f2bf(x2);
;             }
;           }
.LBB0_2094:
	s_or_b64 exec, exec, s[4:5]
	v_add_u32_e32 v0, s16, v184
	v_mov_b64_e32 v[118:119], s[72:73]
	s_movk_i32 s4, 0x1b00
	v_lshlrev_b32_e32 v120, 5, v0
	v_mad_i64_i32 v[118:119], s[4:5], v0, s4, v[118:119]
	v_and_b32_e32 v120, 0x1f380, v120
	v_or_b32_e32 v121, v120, v186
	v_add_u32_e32 v161, 0x1000, v160
	v_readlane_b32 s4, v252, 58
	v_readlane_b32 s5, v252, 59
	s_nop 4
	global_load_dword v144, v161, s[4:5]
	global_load_dword v145, v161, s[4:5] offset:64
	global_load_dword v146, v161, s[4:5] offset:128
	global_load_dword v147, v161, s[4:5] offset:192
	global_load_dword v148, v161, s[4:5] offset:256
	global_load_dword v149, v161, s[4:5] offset:320
	global_load_dword v150, v161, s[4:5] offset:384
	global_load_dword v151, v161, s[4:5] offset:448
	v_readlane_b32 s4, v252, 60
	v_readlane_b32 s5, v252, 61
	s_nop 4
	global_load_dword v152, v161, s[4:5]
	global_load_dword v153, v161, s[4:5] offset:64
	global_load_dword v154, v161, s[4:5] offset:128
	global_load_dword v155, v161, s[4:5] offset:192
	global_load_dword v156, v161, s[4:5] offset:256
	global_load_dword v157, v161, s[4:5] offset:320
	global_load_dword v158, v161, s[4:5] offset:384
	global_load_dword v159, v161, s[4:5] offset:448
	s_waitcnt vmcnt(32)
	v_readlane_b32 s4, v252, 58
	v_lshlrev_b32_e32 v121, 2, v121
	v_readlane_b32 s5, v252, 59
	s_nop 4
	v_mov_b32_e32 v124, v162
	v_readlane_b32 s4, v252, 60
	v_readlane_b32 s5, v252, 61
	s_nop 4
	v_mov_b32_e32 v121, v170
	v_mul_f32_e32 v122, v114, v121
	v_mul_f32_e32 v121, v26, v121
	v_fma_f32 v122, v26, v124, -v122
	v_fmac_f32_e32 v121, v114, v124
	v_cvt_pk_bf16_f32 v125, v122, s0
	v_lshl_add_u64 v[122:123], v[132:133], 1, v[118:119]
	v_cvt_pk_bf16_f32 v121, v121, s0
	global_store_short v[122:123], v125, off
	global_store_short v[122:123], v121, off offset:64
	s_and_saveexec_b64 s[4:5], s[10:11]
	s_cbranch_execz .LBB0_2096
	v_cvt_pk_bf16_f32 v121, v26, s0
	v_lshl_add_u64 v[122:123], v[134:135], 1, v[118:119]
	v_cvt_pk_bf16_f32 v114, v114, s0
	global_store_short v[122:123], v121, off
	global_store_short v[122:123], v114, off offset:64
.LBB0_2096:
	s_or_b64 exec, exec, s[4:5]
	v_or_b32_e32 v114, v120, v240
	v_readlane_b32 s4, v252, 58
	v_lshlrev_b32_e32 v114, 2, v114
	v_readlane_b32 s5, v252, 59
	s_nop 4
	v_mov_b32_e32 v122, v163
	v_readlane_b32 s4, v252, 60
	v_readlane_b32 s5, v252, 61
	s_nop 4
	v_mov_b32_e32 v114, v171
	v_mul_f32_e32 v120, v106, v114
	v_mul_f32_e32 v114, v110, v114
	v_fma_f32 v120, v110, v122, -v120
	v_fmac_f32_e32 v114, v106, v122
	v_cvt_pk_bf16_f32 v123, v120, s0
	v_lshl_add_u64 v[120:121], v[136:137], 1, v[118:119]
	v_cvt_pk_bf16_f32 v114, v114, s0
	global_store_short v[120:121], v123, off offset:32
	global_store_short v[120:121], v114, off offset:96
	s_and_saveexec_b64 s[4:5], s[10:11]
	s_cbranch_execz .LBB0_2098
	v_lshl_add_u64 v[120:121], v[130:131], 0, v[186:187]
	v_cvt_pk_bf16_f32 v110, v110, s0
	v_lshl_add_u64 v[118:119], v[120:121], 1, v[118:119]
	v_cvt_pk_bf16_f32 v106, v106, s0
	global_store_short v[118:119], v110, off offset:32
	global_store_short v[118:119], v106, off offset:96
.LBB0_2098:
	s_or_b64 exec, exec, s[4:5]
	v_or_b32_e32 v106, 1, v0
	v_mov_b64_e32 v[118:119], s[72:73]
	s_movk_i32 s4, 0x1b00
	v_mad_i64_i32 v[118:119], s[4:5], v106, s4, v[118:119]
	v_lshlrev_b32_e32 v106, 5, v106
	v_and_b32_e32 v106, 0x1ffe0, v106
	v_or_b32_e32 v110, v106, v186
	v_readlane_b32 s4, v252, 58
	v_lshlrev_b32_e32 v110, 2, v110
	v_readlane_b32 s5, v252, 59
	s_nop 4
	v_mov_b32_e32 v114, v164
	v_readlane_b32 s4, v252, 60
	v_readlane_b32 s5, v252, 61
	s_nop 4
	v_mov_b32_e32 v110, v172
	v_mul_f32_e32 v120, v115, v110
	v_mul_f32_e32 v110, v27, v110
	v_fma_f32 v120, v27, v114, -v120
	v_fmac_f32_e32 v110, v115, v114
	v_cvt_pk_bf16_f32 v122, v120, s0
	v_lshl_add_u64 v[120:121], v[132:133], 1, v[118:119]
	v_cvt_pk_bf16_f32 v110, v110, s0
	global_store_short v[120:121], v122, off
	global_store_short v[120:121], v110, off offset:64
	s_and_saveexec_b64 s[4:5], s[10:11]
	s_cbranch_execz .LBB0_2100
	v_cvt_pk_bf16_f32 v110, v27, s0
	v_cvt_pk_bf16_f32 v120, v115, s0
	v_lshl_add_u64 v[114:115], v[134:135], 1, v[118:119]
	global_store_short v[114:115], v110, off
	global_store_short v[114:115], v120, off offset:64
.LBB0_2100:
	s_or_b64 exec, exec, s[4:5]
	v_or_b32_e32 v106, v106, v240
	v_readlane_b32 s4, v252, 58
	v_lshlrev_b32_e32 v106, 2, v106
	v_readlane_b32 s5, v252, 59
	s_nop 4
	v_mov_b32_e32 v110, v165
	v_readlane_b32 s4, v252, 60
	v_readlane_b32 s5, v252, 61
	s_nop 4
	v_mov_b32_e32 v106, v173
	v_mul_f32_e32 v114, v107, v106
	v_mul_f32_e32 v106, v111, v106
	v_fma_f32 v114, v111, v110, -v114
	v_fmac_f32_e32 v106, v107, v110
	v_cvt_pk_bf16_f32 v120, v114, s0
	v_lshl_add_u64 v[114:115], v[136:137], 1, v[118:119]
	v_cvt_pk_bf16_f32 v106, v106, s0
	global_store_short v[114:115], v120, off offset:32
	global_store_short v[114:115], v106, off offset:96
	s_and_saveexec_b64 s[4:5], s[10:11]
	s_cbranch_execz .LBB0_2102
	v_cvt_pk_bf16_f32 v110, v111, s0
	v_cvt_pk_bf16_f32 v111, v107, s0
	v_lshl_add_u64 v[106:107], v[130:131], 0, v[186:187]
	v_lshl_add_u64 v[106:107], v[106:107], 1, v[118:119]
	global_store_short v[106:107], v110, off offset:32
	global_store_short v[106:107], v111, off offset:96
; DEV u16 f2bf(float f) { return (u16)(pack2(f, 0.f) & 0xffffu); }
; DEV void phase_win(const Params& P, int l, const u16* __restrict__ xb, const u16* __restrict__ Wt, u16* __restrict__ h, char* smem) {
;     ...
;       for (int ms = 0; ms < 8; ++ms) {
;       asm volatile("" ::: "memory");
; #pragma unroll
;         for (int j = 0; j < 4; ++j) {
;           int row = m0 + wm * 128 + ms * 16 + quad * 4 + j;
;           int pos = row & (S - 1);
;           u16* hr = h + (size_t)row * HS;
; #pragma unroll
;           for (int ns = 0; ns < 2; ++ns) {
;             int d1 = ns * 16 + l15;
;             float x1 = acc[ms][ns][j], x2 = acc[ms][ns + 2][j];
;             float cs = cosT[pos * 32 + d1], sn = sinT[pos * 32 + d1];
;             hr[dst + d1] = f2bf(x1 * cs - x2 * sn);
;             hr[dst + d1 + 32] = f2bf(x1 * sn + x2 * cs);
;             if (cb < 256) {
;               hr[cb + d1] = f2bf(x1);
;               hr[cb + d1 + 32] = f2bf(x2);
;             }
;           }
.LBB0_2102:
	s_or_b64 exec, exec, s[4:5]
	v_or_b32_e32 v110, 2, v0
	v_mov_b64_e32 v[106:107], s[72:73]
	s_movk_i32 s4, 0x1b00
	v_mad_i64_i32 v[106:107], s[4:5], v110, s4, v[106:107]
	v_lshlrev_b32_e32 v110, 5, v110
	v_and_b32_e32 v110, 0x1ffe0, v110
	v_or_b32_e32 v111, v110, v186
	v_readlane_b32 s4, v252, 58
	v_lshlrev_b32_e32 v111, 2, v111
	v_readlane_b32 s5, v252, 59
	s_nop 4
	v_mov_b32_e32 v118, v166
	v_readlane_b32 s4, v252, 60
	v_readlane_b32 s5, v252, 61
	s_nop 4
	v_mov_b32_e32 v111, v174
	v_mul_f32_e32 v114, v116, v111
	v_mul_f32_e32 v111, v28, v111
	v_fma_f32 v114, v28, v118, -v114
	v_fmac_f32_e32 v111, v116, v118
	v_cvt_pk_bf16_f32 v119, v114, s0
	v_lshl_add_u64 v[114:115], v[132:133], 1, v[106:107]
	v_cvt_pk_bf16_f32 v111, v111, s0
	global_store_short v[114:115], v119, off
	global_store_short v[114:115], v111, off offset:64
	s_and_saveexec_b64 s[4:5], s[10:11]
	s_cbranch_execz .LBB0_2104
	v_cvt_pk_bf16_f32 v111, v28, s0
	v_lshl_add_u64 v[114:115], v[134:135], 1, v[106:107]
	v_cvt_pk_bf16_f32 v116, v116, s0
	global_store_short v[114:115], v111, off
	global_store_short v[114:115], v116, off offset:64
.LBB0_2104:
	s_or_b64 exec, exec, s[4:5]
	v_or_b32_e32 v110, v110, v240
	v_readlane_b32 s4, v252, 58
	v_lshlrev_b32_e32 v110, 2, v110
	v_readlane_b32 s5, v252, 59
	s_nop 4
	v_mov_b32_e32 v114, v167
	v_readlane_b32 s4, v252, 60
	v_readlane_b32 s5, v252, 61
	s_nop 4
	v_mov_b32_e32 v115, v175
	v_mul_f32_e32 v110, v108, v115
	v_mul_f32_e32 v115, v112, v115
	v_fma_f32 v110, v112, v114, -v110
	v_fmac_f32_e32 v115, v108, v114
	v_cvt_pk_bf16_f32 v116, v110, s0
	v_lshl_add_u64 v[110:111], v[136:137], 1, v[106:107]
	v_cvt_pk_bf16_f32 v114, v115, s0
	global_store_short v[110:111], v116, off offset:32
	global_store_short v[110:111], v114, off offset:96
	s_and_saveexec_b64 s[4:5], s[10:11]
	s_cbranch_execz .LBB0_2106
	v_lshl_add_u64 v[110:111], v[130:131], 0, v[186:187]
	v_cvt_pk_bf16_f32 v112, v112, s0
	v_lshl_add_u64 v[106:107], v[110:111], 1, v[106:107]
	v_cvt_pk_bf16_f32 v108, v108, s0
	global_store_short v[106:107], v112, off offset:32
	global_store_short v[106:107], v108, off offset:96
.LBB0_2106:
	s_or_b64 exec, exec, s[4:5]
	v_or_b32_e32 v0, 3, v0
	v_mov_b64_e32 v[106:107], s[72:73]
	s_movk_i32 s4, 0x1b00
	v_mad_i64_i32 v[106:107], s[4:5], v0, s4, v[106:107]
	v_lshlrev_b32_e32 v0, 5, v0
	v_and_b32_e32 v0, 0x1ffe0, v0
	v_or_b32_e32 v108, v0, v186
	v_readlane_b32 s4, v252, 58
	v_lshlrev_b32_e32 v108, 2, v108
	v_readlane_b32 s5, v252, 59
	s_nop 4
	v_mov_b32_e32 v112, v168
	v_readlane_b32 s4, v252, 60
	v_readlane_b32 s5, v252, 61
	s_nop 4
	v_mov_b32_e32 v108, v176
	v_mul_f32_e32 v110, v117, v108
	v_mul_f32_e32 v108, v29, v108
	v_fma_f32 v110, v29, v112, -v110
	v_fmac_f32_e32 v108, v117, v112
	v_cvt_pk_bf16_f32 v114, v110, s0
	v_lshl_add_u64 v[110:111], v[132:133], 1, v[106:107]
	v_cvt_pk_bf16_f32 v108, v108, s0
	global_store_short v[110:111], v114, off
	global_store_short v[110:111], v108, off offset:64
	s_and_saveexec_b64 s[4:5], s[10:11]
	s_cbranch_execz .LBB0_2108
	v_cvt_pk_bf16_f32 v108, v29, s0
	v_lshl_add_u64 v[110:111], v[134:135], 1, v[106:107]
	v_cvt_pk_bf16_f32 v112, v117, s0
	global_store_short v[110:111], v108, off
	global_store_short v[110:111], v112, off offset:64
.LBB0_2108:
	s_or_b64 exec, exec, s[4:5]
	v_or_b32_e32 v0, v0, v240
	v_readlane_b32 s4, v252, 58
	v_lshlrev_b32_e32 v0, 2, v0
	v_readlane_b32 s5, v252, 59
	s_nop 4
	v_mov_b32_e32 v108, v169
	v_readlane_b32 s4, v252, 60
	v_readlane_b32 s5, v252, 61
	s_nop 4
	v_mov_b32_e32 v0, v177
	v_mul_f32_e32 v110, v109, v0
	v_mul_f32_e32 v0, v113, v0
	v_fma_f32 v110, v113, v108, -v110
	v_fmac_f32_e32 v0, v109, v108
	v_cvt_pk_bf16_f32 v112, v110, s0
	v_lshl_add_u64 v[110:111], v[136:137], 1, v[106:107]
	v_cvt_pk_bf16_f32 v0, v0, s0
	global_store_short v[110:111], v112, off offset:32
	global_store_short v[110:111], v0, off offset:96
	s_and_saveexec_b64 s[4:5], s[10:11]
	s_cbranch_execz .LBB0_2110
	v_cvt_pk_bf16_f32 v110, v109, s0
	v_lshl_add_u64 v[108:109], v[130:131], 0, v[186:187]
	v_cvt_pk_bf16_f32 v0, v113, s0
	v_lshl_add_u64 v[106:107], v[108:109], 1, v[106:107]
	global_store_short v[106:107], v0, off offset:32
	global_store_short v[106:107], v110, off offset:96
.LBB0_2110:
	s_or_b64 exec, exec, s[4:5]
	v_add_u32_e32 v0, s16, v234
	v_mov_b64_e32 v[106:107], s[72:73]
	s_movk_i32 s4, 0x1b00
	v_lshlrev_b32_e32 v108, 5, v0
	v_mad_i64_i32 v[106:107], s[4:5], v0, s4, v[106:107]
	v_and_b32_e32 v108, 0x1f580, v108
	v_or_b32_e32 v109, v108, v186
	v_add_u32_e32 v161, 0x1800, v160
	v_readlane_b32 s4, v252, 58
	v_readlane_b32 s5, v252, 59
	s_nop 4
	global_load_dword v162, v161, s[4:5]
	global_load_dword v163, v161, s[4:5] offset:64
	global_load_dword v164, v161, s[4:5] offset:128
	global_load_dword v165, v161, s[4:5] offset:192
	global_load_dword v166, v161, s[4:5] offset:256
	global_load_dword v167, v161, s[4:5] offset:320
	global_load_dword v168, v161, s[4:5] offset:384
	global_load_dword v169, v161, s[4:5] offset:448
	v_readlane_b32 s4, v252, 60
	v_readlane_b32 s5, v252, 61
	s_nop 4
	global_load_dword v170, v161, s[4:5]
	global_load_dword v171, v161, s[4:5] offset:64
	global_load_dword v172, v161, s[4:5] offset:128
	global_load_dword v173, v161, s[4:5] offset:192
	global_load_dword v174, v161, s[4:5] offset:256
	global_load_dword v175, v161, s[4:5] offset:320
	global_load_dword v176, v161, s[4:5] offset:384
	global_load_dword v177, v161, s[4:5] offset:448
	s_waitcnt vmcnt(32)
	v_readlane_b32 s4, v252, 58
	v_lshlrev_b32_e32 v109, 2, v109
	v_readlane_b32 s5, v252, 59
	s_nop 4
	v_mov_b32_e32 v112, v144
	v_readlane_b32 s4, v252, 60
	v_readlane_b32 s5, v252, 61
	s_nop 4
	v_mov_b32_e32 v109, v152
	v_mul_f32_e32 v110, v102, v109
	v_mul_f32_e32 v109, v22, v109
	v_fma_f32 v110, v22, v112, -v110
	v_fmac_f32_e32 v109, v102, v112
	v_cvt_pk_bf16_f32 v113, v110, s0
	v_lshl_add_u64 v[110:111], v[132:133], 1, v[106:107]
	v_cvt_pk_bf16_f32 v109, v109, s0
	global_store_short v[110:111], v113, off
	global_store_short v[110:111], v109, off offset:64
	s_and_saveexec_b64 s[4:5], s[10:11]
	s_cbranch_execz .LBB0_2112
	v_cvt_pk_bf16_f32 v109, v22, s0
	v_lshl_add_u64 v[110:111], v[134:135], 1, v[106:107]
	v_cvt_pk_bf16_f32 v102, v102, s0
	global_store_short v[110:111], v109, off
	global_store_short v[110:111], v102, off offset:64

; DEV u16 f2bf(float f) { return (u16)(pack2(f, 0.f) & 0xffffu); }
; DEV void phase_win(const Params& P, int l, const u16* __restrict__ xb, const u16* __restrict__ Wt, u16* __restrict__ h, char* smem) {
;     ...
;       for (int ms = 0; ms < 8; ++ms) {
;       asm volatile("" ::: "memory");
; #pragma unroll
;         for (int j = 0; j < 4; ++j) {
;           int row = m0 + wm * 128 + ms * 16 + quad * 4 + j;
;           int pos = row & (S - 1);
;           u16* hr = h + (size_t)row * HS;
; #pragma unroll
;           for (int ns = 0; ns < 2; ++ns) {
;             int d1 = ns * 16 + l15;
;             float x1 = acc[ms][ns][j], x2 = acc[ms][ns + 2][j];
;             float cs = cosT[pos * 32 + d1], sn = sinT[pos * 32 + d1];
;             hr[dst + d1] = f2bf(x1 * cs - x2 * sn);
;             hr[dst + d1 + 32] = f2bf(x1 * sn + x2 * cs);
;             if (cb < 256) {
;               hr[cb + d1] = f2bf(x1);
;               hr[cb + d1 + 32] = f2bf(x2);
;             }
;           }
.LBB0_2126:
	s_or_b64 exec, exec, s[4:5]
	v_add_u32_e32 v0, s16, v235
	v_mov_b64_e32 v[94:95], s[72:73]
	s_movk_i32 s4, 0x1b00
	v_lshlrev_b32_e32 v96, 5, v0
	v_mad_i64_i32 v[94:95], s[4:5], v0, s4, v[94:95]
	v_and_b32_e32 v96, 0x1f780, v96
	v_or_b32_e32 v97, v96, v186
	v_add_u32_e32 v161, 0x2000, v160
	v_readlane_b32 s4, v252, 58
	v_readlane_b32 s5, v252, 59
	s_nop 4
	global_load_dword v144, v161, s[4:5]
	global_load_dword v145, v161, s[4:5] offset:64
	global_load_dword v146, v161, s[4:5] offset:128
	global_load_dword v147, v161, s[4:5] offset:192
	global_load_dword v148, v161, s[4:5] offset:256
	global_load_dword v149, v161, s[4:5] offset:320
	global_load_dword v150, v161, s[4:5] offset:384
	global_load_dword v151, v161, s[4:5] offset:448
	v_readlane_b32 s4, v252, 60
	v_readlane_b32 s5, v252, 61
	s_nop 4
	global_load_dword v152, v161, s[4:5]
	global_load_dword v153, v161, s[4:5] offset:64
	global_load_dword v154, v161, s[4:5] offset:128
	global_load_dword v155, v161, s[4:5] offset:192
	global_load_dword v156, v161, s[4:5] offset:256
	global_load_dword v157, v161, s[4:5] offset:320
	global_load_dword v158, v161, s[4:5] offset:384
	global_load_dword v159, v161, s[4:5] offset:448
	s_waitcnt vmcnt(32)
	v_readlane_b32 s4, v252, 58
	v_lshlrev_b32_e32 v97, 2, v97
	v_readlane_b32 s5, v252, 59
	s_nop 4
	v_mov_b32_e32 v100, v162
	v_readlane_b32 s4, v252, 60
	v_readlane_b32 s5, v252, 61
	s_nop 4
	v_mov_b32_e32 v97, v170
	v_mul_f32_e32 v98, v90, v97
	v_mul_f32_e32 v97, v18, v97
	v_fma_f32 v98, v18, v100, -v98
	v_fmac_f32_e32 v97, v90, v100
	v_cvt_pk_bf16_f32 v101, v98, s0
	v_lshl_add_u64 v[98:99], v[132:133], 1, v[94:95]
	v_cvt_pk_bf16_f32 v97, v97, s0
	global_store_short v[98:99], v101, off
	global_store_short v[98:99], v97, off offset:64
	s_and_saveexec_b64 s[4:5], s[10:11]
	s_cbranch_execz .LBB0_2128
	v_cvt_pk_bf16_f32 v97, v18, s0
	v_lshl_add_u64 v[98:99], v[134:135], 1, v[94:95]
	v_cvt_pk_bf16_f32 v90, v90, s0
	global_store_short v[98:99], v97, off
	global_store_short v[98:99], v90, off offset:64
.LBB0_2128:
	s_or_b64 exec, exec, s[4:5]
	v_or_b32_e32 v90, v96, v240
	v_readlane_b32 s4, v252, 58
	v_lshlrev_b32_e32 v90, 2, v90
	v_readlane_b32 s5, v252, 59
	s_nop 4
	v_mov_b32_e32 v98, v163
	v_readlane_b32 s4, v252, 60
	v_readlane_b32 s5, v252, 61
	s_nop 4
	v_mov_b32_e32 v90, v171
	v_mul_f32_e32 v96, v82, v90
	v_mul_f32_e32 v90, v86, v90
	v_fma_f32 v96, v86, v98, -v96
	v_fmac_f32_e32 v90, v82, v98
	v_cvt_pk_bf16_f32 v99, v96, s0
	v_lshl_add_u64 v[96:97], v[136:137], 1, v[94:95]
	v_cvt_pk_bf16_f32 v90, v90, s0
	global_store_short v[96:97], v99, off offset:32
	global_store_short v[96:97], v90, off offset:96
	s_and_saveexec_b64 s[4:5], s[10:11]
	s_cbranch_execz .LBB0_2130
	v_lshl_add_u64 v[96:97], v[130:131], 0, v[186:187]
	v_cvt_pk_bf16_f32 v86, v86, s0
	v_lshl_add_u64 v[94:95], v[96:97], 1, v[94:95]
	v_cvt_pk_bf16_f32 v82, v82, s0
	global_store_short v[94:95], v86, off offset:32
	global_store_short v[94:95], v82, off offset:96
.LBB0_2130:
	s_or_b64 exec, exec, s[4:5]
	v_or_b32_e32 v82, 1, v0
	v_mov_b64_e32 v[94:95], s[72:73]
	s_movk_i32 s4, 0x1b00
	v_mad_i64_i32 v[94:95], s[4:5], v82, s4, v[94:95]
	v_lshlrev_b32_e32 v82, 5, v82
	v_and_b32_e32 v82, 0x1ffe0, v82
	v_or_b32_e32 v86, v82, v186
	v_readlane_b32 s4, v252, 58
	v_lshlrev_b32_e32 v86, 2, v86
	v_readlane_b32 s5, v252, 59
	s_nop 4
	v_mov_b32_e32 v90, v164
	v_readlane_b32 s4, v252, 60
	v_readlane_b32 s5, v252, 61
	s_nop 4
	v_mov_b32_e32 v86, v172
	v_mul_f32_e32 v96, v91, v86
	v_mul_f32_e32 v86, v19, v86
	v_fma_f32 v96, v19, v90, -v96
	v_fmac_f32_e32 v86, v91, v90
	v_cvt_pk_bf16_f32 v98, v96, s0
	v_lshl_add_u64 v[96:97], v[132:133], 1, v[94:95]
	v_cvt_pk_bf16_f32 v86, v86, s0
	global_store_short v[96:97], v98, off
	global_store_short v[96:97], v86, off offset:64
	s_and_saveexec_b64 s[4:5], s[10:11]
	s_cbranch_execz .LBB0_2132
	v_cvt_pk_bf16_f32 v86, v19, s0
	v_cvt_pk_bf16_f32 v96, v91, s0
	v_lshl_add_u64 v[90:91], v[134:135], 1, v[94:95]
	global_store_short v[90:91], v86, off
	global_store_short v[90:91], v96, off offset:64
.LBB0_2132:
	s_or_b64 exec, exec, s[4:5]
	v_or_b32_e32 v82, v82, v240
	v_readlane_b32 s4, v252, 58
	v_lshlrev_b32_e32 v82, 2, v82
	v_readlane_b32 s5, v252, 59
	s_nop 4
	v_mov_b32_e32 v86, v165
	v_readlane_b32 s4, v252, 60
	v_readlane_b32 s5, v252, 61
	s_nop 4
	v_mov_b32_e32 v82, v173
	v_mul_f32_e32 v90, v83, v82
	v_mul_f32_e32 v82, v87, v82
	v_fma_f32 v90, v87, v86, -v90
	v_fmac_f32_e32 v82, v83, v86
	v_cvt_pk_bf16_f32 v96, v90, s0
	v_lshl_add_u64 v[90:91], v[136:137], 1, v[94:95]
	v_cvt_pk_bf16_f32 v82, v82, s0
	global_store_short v[90:91], v96, off offset:32
	global_store_short v[90:91], v82, off offset:96
	s_and_saveexec_b64 s[4:5], s[10:11]
	s_cbranch_execz .LBB0_2134
	v_cvt_pk_bf16_f32 v86, v87, s0
	v_cvt_pk_bf16_f32 v87, v83, s0
	v_lshl_add_u64 v[82:83], v[130:131], 0, v[186:187]
	v_lshl_add_u64 v[82:83], v[82:83], 1, v[94:95]
	global_store_short v[82:83], v86, off offset:32
	global_store_short v[82:83], v87, off offset:96
; DEV u16 f2bf(float f) { return (u16)(pack2(f, 0.f) & 0xffffu); }
; DEV void phase_win(const Params& P, int l, const u16* __restrict__ xb, const u16* __restrict__ Wt, u16* __restrict__ h, char* smem) {
;     ...
;       for (int ms = 0; ms < 8; ++ms) {
;       asm volatile("" ::: "memory");
; #pragma unroll
;         for (int j = 0; j < 4; ++j) {
;           int row = m0 + wm * 128 + ms * 16 + quad * 4 + j;
;           int pos = row & (S - 1);
;           u16* hr = h + (size_t)row * HS;
; #pragma unroll
;           for (int ns = 0; ns < 2; ++ns) {
;             int d1 = ns * 16 + l15;
;             float x1 = acc[ms][ns][j], x2 = acc[ms][ns + 2][j];
;             float cs = cosT[pos * 32 + d1], sn = sinT[pos * 32 + d1];
;             hr[dst + d1] = f2bf(x1 * cs - x2 * sn);
;             hr[dst + d1 + 32] = f2bf(x1 * sn + x2 * cs);
;             if (cb < 256) {
;               hr[cb + d1] = f2bf(x1);
;               hr[cb + d1 + 32] = f2bf(x2);
;             }
;           }
.LBB0_2134:
	s_or_b64 exec, exec, s[4:5]
	v_or_b32_e32 v86, 2, v0
	v_mov_b64_e32 v[82:83], s[72:73]
	s_movk_i32 s4, 0x1b00
	v_mad_i64_i32 v[82:83], s[4:5], v86, s4, v[82:83]
	v_lshlrev_b32_e32 v86, 5, v86
	v_and_b32_e32 v86, 0x1ffe0, v86
	v_or_b32_e32 v87, v86, v186
	v_readlane_b32 s4, v252, 58
	v_lshlrev_b32_e32 v87, 2, v87
	v_readlane_b32 s5, v252, 59
	s_nop 4
	v_mov_b32_e32 v94, v166
	v_readlane_b32 s4, v252, 60
	v_readlane_b32 s5, v252, 61
	s_nop 4
	v_mov_b32_e32 v87, v174
	v_mul_f32_e32 v90, v92, v87
	v_mul_f32_e32 v87, v20, v87
	v_fma_f32 v90, v20, v94, -v90
	v_fmac_f32_e32 v87, v92, v94
	v_cvt_pk_bf16_f32 v95, v90, s0
	v_lshl_add_u64 v[90:91], v[132:133], 1, v[82:83]
	v_cvt_pk_bf16_f32 v87, v87, s0
	global_store_short v[90:91], v95, off
	global_store_short v[90:91], v87, off offset:64
	s_and_saveexec_b64 s[4:5], s[10:11]
	s_cbranch_execz .LBB0_2136
	v_cvt_pk_bf16_f32 v87, v20, s0
	v_lshl_add_u64 v[90:91], v[134:135], 1, v[82:83]
	v_cvt_pk_bf16_f32 v92, v92, s0
	global_store_short v[90:91], v87, off
	global_store_short v[90:91], v92, off offset:64
.LBB0_2136:
	s_or_b64 exec, exec, s[4:5]
	v_or_b32_e32 v86, v86, v240
	v_readlane_b32 s4, v252, 58
	v_lshlrev_b32_e32 v86, 2, v86
	v_readlane_b32 s5, v252, 59
	s_nop 4
	v_mov_b32_e32 v90, v167
	v_readlane_b32 s4, v252, 60
	v_readlane_b32 s5, v252, 61
	s_nop 4
	v_mov_b32_e32 v91, v175
	v_mul_f32_e32 v86, v84, v91
	v_mul_f32_e32 v91, v88, v91
	v_fma_f32 v86, v88, v90, -v86
	v_fmac_f32_e32 v91, v84, v90
	v_cvt_pk_bf16_f32 v92, v86, s0
	v_lshl_add_u64 v[86:87], v[136:137], 1, v[82:83]
	v_cvt_pk_bf16_f32 v90, v91, s0
	global_store_short v[86:87], v92, off offset:32
	global_store_short v[86:87], v90, off offset:96
	s_and_saveexec_b64 s[4:5], s[10:11]
	s_cbranch_execz .LBB0_2138
	v_lshl_add_u64 v[86:87], v[130:131], 0, v[186:187]
	v_cvt_pk_bf16_f32 v88, v88, s0
	v_lshl_add_u64 v[82:83], v[86:87], 1, v[82:83]
	v_cvt_pk_bf16_f32 v84, v84, s0
	global_store_short v[82:83], v88, off offset:32
	global_store_short v[82:83], v84, off offset:96
.LBB0_2138:
	s_or_b64 exec, exec, s[4:5]
	v_or_b32_e32 v0, 3, v0
	v_mov_b64_e32 v[82:83], s[72:73]
	s_movk_i32 s4, 0x1b00
	v_mad_i64_i32 v[82:83], s[4:5], v0, s4, v[82:83]
	v_lshlrev_b32_e32 v0, 5, v0
	v_and_b32_e32 v0, 0x1ffe0, v0
	v_or_b32_e32 v84, v0, v186
	v_readlane_b32 s4, v252, 58
	v_lshlrev_b32_e32 v84, 2, v84
	v_readlane_b32 s5, v252, 59
	s_nop 4
	v_mov_b32_e32 v88, v168
	v_readlane_b32 s4, v252, 60
	v_readlane_b32 s5, v252, 61
	s_nop 4
	v_mov_b32_e32 v84, v176
	v_mul_f32_e32 v86, v93, v84
	v_mul_f32_e32 v84, v21, v84
	v_fma_f32 v86, v21, v88, -v86
	v_fmac_f32_e32 v84, v93, v88
	v_cvt_pk_bf16_f32 v90, v86, s0
	v_lshl_add_u64 v[86:87], v[132:133], 1, v[82:83]
	v_cvt_pk_bf16_f32 v84, v84, s0
	global_store_short v[86:87], v90, off
	global_store_short v[86:87], v84, off offset:64
	s_and_saveexec_b64 s[4:5], s[10:11]
	s_cbranch_execz .LBB0_2140
	v_cvt_pk_bf16_f32 v84, v21, s0
	v_lshl_add_u64 v[86:87], v[134:135], 1, v[82:83]
	v_cvt_pk_bf16_f32 v88, v93, s0
	global_store_short v[86:87], v84, off
	global_store_short v[86:87], v88, off offset:64
.LBB0_2140:
	s_or_b64 exec, exec, s[4:5]
	v_or_b32_e32 v0, v0, v240
	v_readlane_b32 s4, v252, 58
	v_lshlrev_b32_e32 v0, 2, v0
	v_readlane_b32 s5, v252, 59
	s_nop 4
	v_mov_b32_e32 v84, v169
	v_readlane_b32 s4, v252, 60
	v_readlane_b32 s5, v252, 61
	s_nop 4
	v_mov_b32_e32 v0, v177
	v_mul_f32_e32 v86, v85, v0
	v_mul_f32_e32 v0, v89, v0
	v_fma_f32 v86, v89, v84, -v86
	v_fmac_f32_e32 v0, v85, v84
	v_cvt_pk_bf16_f32 v88, v86, s0
	v_lshl_add_u64 v[86:87], v[136:137], 1, v[82:83]
	v_cvt_pk_bf16_f32 v0, v0, s0
	global_store_short v[86:87], v88, off offset:32
	global_store_short v[86:87], v0, off offset:96
	s_and_saveexec_b64 s[4:5], s[10:11]
	s_cbranch_execz .LBB0_2142
	v_cvt_pk_bf16_f32 v86, v85, s0
	v_lshl_add_u64 v[84:85], v[130:131], 0, v[186:187]
	v_cvt_pk_bf16_f32 v0, v89, s0
	v_lshl_add_u64 v[82:83], v[84:85], 1, v[82:83]
	global_store_short v[82:83], v0, off offset:32
	global_store_short v[82:83], v86, off offset:96
.LBB0_2142:
	s_or_b64 exec, exec, s[4:5]
	v_add_u32_e32 v0, s16, v236
	v_mov_b64_e32 v[82:83], s[72:73]
	s_movk_i32 s4, 0x1b00
	v_lshlrev_b32_e32 v84, 5, v0
	v_mad_i64_i32 v[82:83], s[4:5], v0, s4, v[82:83]
	v_and_b32_e32 v84, 0x1f980, v84
	v_or_b32_e32 v85, v84, v186
	v_add_u32_e32 v161, 0x2800, v160
	v_readlane_b32 s4, v252, 58
	v_readlane_b32 s5, v252, 59
	s_nop 4
	global_load_dword v162, v161, s[4:5]
	global_load_dword v163, v161, s[4:5] offset:64
	global_load_dword v164, v161, s[4:5] offset:128
	global_load_dword v165, v161, s[4:5] offset:192
	global_load_dword v166, v161, s[4:5] offset:256
	global_load_dword v167, v161, s[4:5] offset:320
	global_load_dword v168, v161, s[4:5] offset:384
	global_load_dword v169, v161, s[4:5] offset:448
	v_readlane_b32 s4, v252, 60
	v_readlane_b32 s5, v252, 61
	s_nop 4
	global_load_dword v170, v161, s[4:5]
	global_load_dword v171, v161, s[4:5] offset:64
	global_load_dword v172, v161, s[4:5] offset:128
	global_load_dword v173, v161, s[4:5] offset:192
	global_load_dword v174, v161, s[4:5] offset:256
	global_load_dword v175, v161, s[4:5] offset:320
	global_load_dword v176, v161, s[4:5] offset:384
	global_load_dword v177, v161, s[4:5] offset:448
	s_waitcnt vmcnt(32)
	v_readlane_b32 s4, v252, 58
	v_lshlrev_b32_e32 v85, 2, v85
	v_readlane_b32 s5, v252, 59
	s_nop 4
	v_mov_b32_e32 v88, v144
	v_readlane_b32 s4, v252, 60
	v_readlane_b32 s5, v252, 61
	s_nop 4
	v_mov_b32_e32 v85, v152
	v_mul_f32_e32 v86, v78, v85
	v_mul_f32_e32 v85, v14, v85
	v_fma_f32 v86, v14, v88, -v86
	v_fmac_f32_e32 v85, v78, v88
	v_cvt_pk_bf16_f32 v89, v86, s0
	v_lshl_add_u64 v[86:87], v[132:133], 1, v[82:83]
	v_cvt_pk_bf16_f32 v85, v85, s0
	global_store_short v[86:87], v89, off
	global_store_short v[86:87], v85, off offset:64
	s_and_saveexec_b64 s[4:5], s[10:11]
	s_cbranch_execz .LBB0_2144
	v_cvt_pk_bf16_f32 v85, v14, s0
	v_lshl_add_u64 v[86:87], v[134:135], 1, v[82:83]
	v_cvt_pk_bf16_f32 v78, v78, s0
	global_store_short v[86:87], v85, off
	global_store_short v[86:87], v78, off offset:64

; DEV u16 f2bf(float f) { return (u16)(pack2(f, 0.f) & 0xffffu); }
; DEV void phase_win(const Params& P, int l, const u16* __restrict__ xb, const u16* __restrict__ Wt, u16* __restrict__ h, char* smem) {
;     ...
;       for (int ms = 0; ms < 8; ++ms) {
;       asm volatile("" ::: "memory");
; #pragma unroll
;         for (int j = 0; j < 4; ++j) {
;           int row = m0 + wm * 128 + ms * 16 + quad * 4 + j;
;           int pos = row & (S - 1);
;           u16* hr = h + (size_t)row * HS;
; #pragma unroll
;           for (int ns = 0; ns < 2; ++ns) {
;             int d1 = ns * 16 + l15;
;             float x1 = acc[ms][ns][j], x2 = acc[ms][ns + 2][j];
;             float cs = cosT[pos * 32 + d1], sn = sinT[pos * 32 + d1];
;             hr[dst + d1] = f2bf(x1 * cs - x2 * sn);
;             hr[dst + d1 + 32] = f2bf(x1 * sn + x2 * cs);
;             if (cb < 256) {
;               hr[cb + d1] = f2bf(x1);
;               hr[cb + d1 + 32] = f2bf(x2);
;             }
;           }
.LBB0_2158:
	s_or_b64 exec, exec, s[4:5]
	v_add_u32_e32 v0, s16, v237
	v_mov_b64_e32 v[70:71], s[72:73]
	s_movk_i32 s4, 0x1b00
	v_lshlrev_b32_e32 v72, 5, v0
	v_mad_i64_i32 v[70:71], s[4:5], v0, s4, v[70:71]
	v_and_b32_e32 v72, 0x1fb80, v72
	v_or_b32_e32 v73, v72, v186
	v_add_u32_e32 v161, 0x3000, v160
	v_readlane_b32 s4, v252, 58
	v_readlane_b32 s5, v252, 59
	s_nop 4
	global_load_dword v144, v161, s[4:5]
	global_load_dword v145, v161, s[4:5] offset:64
	global_load_dword v146, v161, s[4:5] offset:128
	global_load_dword v147, v161, s[4:5] offset:192
	global_load_dword v148, v161, s[4:5] offset:256
	global_load_dword v149, v161, s[4:5] offset:320
	global_load_dword v150, v161, s[4:5] offset:384
	global_load_dword v151, v161, s[4:5] offset:448
	v_readlane_b32 s4, v252, 60
	v_readlane_b32 s5, v252, 61
	s_nop 4
	global_load_dword v152, v161, s[4:5]
	global_load_dword v153, v161, s[4:5] offset:64
	global_load_dword v154, v161, s[4:5] offset:128
	global_load_dword v155, v161, s[4:5] offset:192
	global_load_dword v156, v161, s[4:5] offset:256
	global_load_dword v157, v161, s[4:5] offset:320
	global_load_dword v158, v161, s[4:5] offset:384
	global_load_dword v159, v161, s[4:5] offset:448
	s_waitcnt vmcnt(32)
	v_readlane_b32 s4, v252, 58
	v_lshlrev_b32_e32 v73, 2, v73
	v_readlane_b32 s5, v252, 59
	s_nop 4
	v_mov_b32_e32 v76, v162
	v_readlane_b32 s4, v252, 60
	v_readlane_b32 s5, v252, 61
	s_nop 4
	v_mov_b32_e32 v73, v170
	v_mul_f32_e32 v74, v66, v73
	v_mul_f32_e32 v73, v10, v73
	v_fma_f32 v74, v10, v76, -v74
	v_fmac_f32_e32 v73, v66, v76
	v_cvt_pk_bf16_f32 v77, v74, s0
	v_lshl_add_u64 v[74:75], v[132:133], 1, v[70:71]
	v_cvt_pk_bf16_f32 v73, v73, s0
	global_store_short v[74:75], v77, off
	global_store_short v[74:75], v73, off offset:64
	s_and_saveexec_b64 s[4:5], s[10:11]
	s_cbranch_execz .LBB0_2160
	v_cvt_pk_bf16_f32 v73, v10, s0
	v_lshl_add_u64 v[74:75], v[134:135], 1, v[70:71]
	v_cvt_pk_bf16_f32 v66, v66, s0
	global_store_short v[74:75], v73, off
	global_store_short v[74:75], v66, off offset:64
.LBB0_2160:
	s_or_b64 exec, exec, s[4:5]
	v_or_b32_e32 v66, v72, v240
	v_readlane_b32 s4, v252, 58
	v_lshlrev_b32_e32 v66, 2, v66
	v_readlane_b32 s5, v252, 59
	s_nop 4
	v_mov_b32_e32 v74, v163
	v_readlane_b32 s4, v252, 60
	v_readlane_b32 s5, v252, 61
	s_nop 4
	v_mov_b32_e32 v66, v171
	v_mul_f32_e32 v72, v58, v66
	v_mul_f32_e32 v66, v62, v66
	v_fma_f32 v72, v62, v74, -v72
	v_fmac_f32_e32 v66, v58, v74
	v_cvt_pk_bf16_f32 v75, v72, s0
	v_lshl_add_u64 v[72:73], v[136:137], 1, v[70:71]
	v_cvt_pk_bf16_f32 v66, v66, s0
	global_store_short v[72:73], v75, off offset:32
	global_store_short v[72:73], v66, off offset:96
	s_and_saveexec_b64 s[4:5], s[10:11]
	s_cbranch_execz .LBB0_2162
	v_lshl_add_u64 v[72:73], v[130:131], 0, v[186:187]
	v_cvt_pk_bf16_f32 v62, v62, s0
	v_lshl_add_u64 v[70:71], v[72:73], 1, v[70:71]
	v_cvt_pk_bf16_f32 v58, v58, s0
	global_store_short v[70:71], v62, off offset:32
	global_store_short v[70:71], v58, off offset:96
.LBB0_2162:
	s_or_b64 exec, exec, s[4:5]
	v_or_b32_e32 v58, 1, v0
	v_mov_b64_e32 v[70:71], s[72:73]
	s_movk_i32 s4, 0x1b00
	v_mad_i64_i32 v[70:71], s[4:5], v58, s4, v[70:71]
	v_lshlrev_b32_e32 v58, 5, v58
	v_and_b32_e32 v58, 0x1ffe0, v58
	v_or_b32_e32 v62, v58, v186
	v_readlane_b32 s4, v252, 58
	v_lshlrev_b32_e32 v62, 2, v62
	v_readlane_b32 s5, v252, 59
	s_nop 4
	v_mov_b32_e32 v66, v164
	v_readlane_b32 s4, v252, 60
	v_readlane_b32 s5, v252, 61
	s_nop 4
	v_mov_b32_e32 v62, v172
	v_mul_f32_e32 v72, v67, v62
	v_mul_f32_e32 v62, v11, v62
	v_fma_f32 v72, v11, v66, -v72
	v_fmac_f32_e32 v62, v67, v66
	v_cvt_pk_bf16_f32 v74, v72, s0
	v_lshl_add_u64 v[72:73], v[132:133], 1, v[70:71]
	v_cvt_pk_bf16_f32 v62, v62, s0
	global_store_short v[72:73], v74, off
	global_store_short v[72:73], v62, off offset:64
	s_and_saveexec_b64 s[4:5], s[10:11]
	s_cbranch_execz .LBB0_2164
	v_cvt_pk_bf16_f32 v62, v11, s0
	v_cvt_pk_bf16_f32 v72, v67, s0
	v_lshl_add_u64 v[66:67], v[134:135], 1, v[70:71]
	global_store_short v[66:67], v62, off
	global_store_short v[66:67], v72, off offset:64
.LBB0_2164:
	s_or_b64 exec, exec, s[4:5]
	v_or_b32_e32 v58, v58, v240
	v_readlane_b32 s4, v252, 58
	v_lshlrev_b32_e32 v58, 2, v58
	v_readlane_b32 s5, v252, 59
	s_nop 4
	v_mov_b32_e32 v62, v165
	v_readlane_b32 s4, v252, 60
	v_readlane_b32 s5, v252, 61
	s_nop 4
	v_mov_b32_e32 v58, v173
	v_mul_f32_e32 v66, v59, v58
	v_mul_f32_e32 v58, v63, v58
	v_fma_f32 v66, v63, v62, -v66
	v_fmac_f32_e32 v58, v59, v62
	v_cvt_pk_bf16_f32 v72, v66, s0
	v_lshl_add_u64 v[66:67], v[136:137], 1, v[70:71]
	v_cvt_pk_bf16_f32 v58, v58, s0
	global_store_short v[66:67], v72, off offset:32
	global_store_short v[66:67], v58, off offset:96
	s_and_saveexec_b64 s[4:5], s[10:11]
	s_cbranch_execz .LBB0_2166
	v_cvt_pk_bf16_f32 v62, v63, s0
	v_cvt_pk_bf16_f32 v63, v59, s0
	v_lshl_add_u64 v[58:59], v[130:131], 0, v[186:187]
	v_lshl_add_u64 v[58:59], v[58:59], 1, v[70:71]
	global_store_short v[58:59], v62, off offset:32
	global_store_short v[58:59], v63, off offset:96
; DEV u16 f2bf(float f) { return (u16)(pack2(f, 0.f) & 0xffffu); }
; DEV void phase_win(const Params& P, int l, const u16* __restrict__ xb, const u16* __restrict__ Wt, u16* __restrict__ h, char* smem) {
;     ...
;       for (int ms = 0; ms < 8; ++ms) {
;       asm volatile("" ::: "memory");
; #pragma unroll
;         for (int j = 0; j < 4; ++j) {
;           int row = m0 + wm * 128 + ms * 16 + quad * 4 + j;
;           int pos = row & (S - 1);
;           u16* hr = h + (size_t)row * HS;
; #pragma unroll
;           for (int ns = 0; ns < 2; ++ns) {
;             int d1 = ns * 16 + l15;
;             float x1 = acc[ms][ns][j], x2 = acc[ms][ns + 2][j];
;             float cs = cosT[pos * 32 + d1], sn = sinT[pos * 32 + d1];
;             hr[dst + d1] = f2bf(x1 * cs - x2 * sn);
;             hr[dst + d1 + 32] = f2bf(x1 * sn + x2 * cs);
;             if (cb < 256) {
;               hr[cb + d1] = f2bf(x1);
;               hr[cb + d1 + 32] = f2bf(x2);
;             }
;           }
.LBB0_2166:
	s_or_b64 exec, exec, s[4:5]
	v_or_b32_e32 v62, 2, v0
	v_mov_b64_e32 v[58:59], s[72:73]
	s_movk_i32 s4, 0x1b00
	v_mad_i64_i32 v[58:59], s[4:5], v62, s4, v[58:59]
	v_lshlrev_b32_e32 v62, 5, v62
	v_and_b32_e32 v62, 0x1ffe0, v62
	v_or_b32_e32 v63, v62, v186
	v_readlane_b32 s4, v252, 58
	v_lshlrev_b32_e32 v63, 2, v63
	v_readlane_b32 s5, v252, 59
	s_nop 4
	v_mov_b32_e32 v70, v166
	v_readlane_b32 s4, v252, 60
	v_readlane_b32 s5, v252, 61
	s_nop 4
	v_mov_b32_e32 v63, v174
	v_mul_f32_e32 v66, v68, v63
	v_mul_f32_e32 v63, v12, v63
	v_fma_f32 v66, v12, v70, -v66
	v_fmac_f32_e32 v63, v68, v70
	v_cvt_pk_bf16_f32 v71, v66, s0
	v_lshl_add_u64 v[66:67], v[132:133], 1, v[58:59]
	v_cvt_pk_bf16_f32 v63, v63, s0
	global_store_short v[66:67], v71, off
	global_store_short v[66:67], v63, off offset:64
	s_and_saveexec_b64 s[4:5], s[10:11]
	s_cbranch_execz .LBB0_2168
	v_cvt_pk_bf16_f32 v63, v12, s0
	v_lshl_add_u64 v[66:67], v[134:135], 1, v[58:59]
	v_cvt_pk_bf16_f32 v68, v68, s0
	global_store_short v[66:67], v63, off
	global_store_short v[66:67], v68, off offset:64
.LBB0_2168:
	s_or_b64 exec, exec, s[4:5]
	v_or_b32_e32 v62, v62, v240
	v_readlane_b32 s4, v252, 58
	v_lshlrev_b32_e32 v62, 2, v62
	v_readlane_b32 s5, v252, 59
	s_nop 4
	v_mov_b32_e32 v66, v167
	v_readlane_b32 s4, v252, 60
	v_readlane_b32 s5, v252, 61
	s_nop 4
	v_mov_b32_e32 v67, v175
	v_mul_f32_e32 v62, v60, v67
	v_mul_f32_e32 v67, v64, v67
	v_fma_f32 v62, v64, v66, -v62
	v_fmac_f32_e32 v67, v60, v66
	v_cvt_pk_bf16_f32 v68, v62, s0
	v_lshl_add_u64 v[62:63], v[136:137], 1, v[58:59]
	v_cvt_pk_bf16_f32 v66, v67, s0
	global_store_short v[62:63], v68, off offset:32
	global_store_short v[62:63], v66, off offset:96
	s_and_saveexec_b64 s[4:5], s[10:11]
	s_cbranch_execz .LBB0_2170
	v_lshl_add_u64 v[62:63], v[130:131], 0, v[186:187]
	v_cvt_pk_bf16_f32 v64, v64, s0
	v_lshl_add_u64 v[58:59], v[62:63], 1, v[58:59]
	v_cvt_pk_bf16_f32 v60, v60, s0
	global_store_short v[58:59], v64, off offset:32
	global_store_short v[58:59], v60, off offset:96
.LBB0_2170:
	s_or_b64 exec, exec, s[4:5]
	v_or_b32_e32 v0, 3, v0
	v_mov_b64_e32 v[58:59], s[72:73]
	s_movk_i32 s4, 0x1b00
	v_mad_i64_i32 v[58:59], s[4:5], v0, s4, v[58:59]
	v_lshlrev_b32_e32 v0, 5, v0
	v_and_b32_e32 v0, 0x1ffe0, v0
	v_or_b32_e32 v60, v0, v186
	v_readlane_b32 s4, v252, 58
	v_lshlrev_b32_e32 v60, 2, v60
	v_readlane_b32 s5, v252, 59
	s_nop 4
	v_mov_b32_e32 v64, v168
	v_readlane_b32 s4, v252, 60
	v_readlane_b32 s5, v252, 61
	s_nop 4
	v_mov_b32_e32 v60, v176
	v_mul_f32_e32 v62, v69, v60
	v_mul_f32_e32 v60, v13, v60
	v_fma_f32 v62, v13, v64, -v62
	v_fmac_f32_e32 v60, v69, v64
	v_cvt_pk_bf16_f32 v66, v62, s0
	v_lshl_add_u64 v[62:63], v[132:133], 1, v[58:59]
	v_cvt_pk_bf16_f32 v60, v60, s0
	global_store_short v[62:63], v66, off
	global_store_short v[62:63], v60, off offset:64
	s_and_saveexec_b64 s[4:5], s[10:11]
	s_cbranch_execz .LBB0_2172
	v_cvt_pk_bf16_f32 v60, v13, s0
	v_lshl_add_u64 v[62:63], v[134:135], 1, v[58:59]
	v_cvt_pk_bf16_f32 v64, v69, s0
	global_store_short v[62:63], v60, off
	global_store_short v[62:63], v64, off offset:64
.LBB0_2172:
	s_or_b64 exec, exec, s[4:5]
	v_or_b32_e32 v0, v0, v240
	v_readlane_b32 s4, v252, 58
	v_lshlrev_b32_e32 v0, 2, v0
	v_readlane_b32 s5, v252, 59
	s_nop 4
	v_mov_b32_e32 v60, v169
	v_readlane_b32 s4, v252, 60
	v_readlane_b32 s5, v252, 61
	s_nop 4
	v_mov_b32_e32 v0, v177
	v_mul_f32_e32 v62, v61, v0
	v_mul_f32_e32 v0, v65, v0
	v_fma_f32 v62, v65, v60, -v62
	v_fmac_f32_e32 v0, v61, v60
	v_cvt_pk_bf16_f32 v64, v62, s0
	v_lshl_add_u64 v[62:63], v[136:137], 1, v[58:59]
	v_cvt_pk_bf16_f32 v0, v0, s0
	global_store_short v[62:63], v64, off offset:32
	global_store_short v[62:63], v0, off offset:96
	s_and_saveexec_b64 s[4:5], s[10:11]
	s_cbranch_execz .LBB0_2174
	v_cvt_pk_bf16_f32 v62, v61, s0
	v_lshl_add_u64 v[60:61], v[130:131], 0, v[186:187]
	v_cvt_pk_bf16_f32 v0, v65, s0
	v_lshl_add_u64 v[58:59], v[60:61], 1, v[58:59]
	global_store_short v[58:59], v0, off offset:32
	global_store_short v[58:59], v62, off offset:96
.LBB0_2174:
	s_or_b64 exec, exec, s[4:5]
	v_add_u32_e32 v0, s16, v238
	v_mov_b64_e32 v[58:59], s[72:73]
	s_movk_i32 s4, 0x1b00
	v_lshlrev_b32_e32 v60, 5, v0
	v_mad_i64_i32 v[58:59], s[4:5], v0, s4, v[58:59]
	v_and_b32_e32 v60, 0x1fd80, v60
	v_or_b32_e32 v61, v60, v186
	v_add_u32_e32 v161, 0x3800, v160
	v_readlane_b32 s4, v252, 58
	v_readlane_b32 s5, v252, 59
	s_nop 4
	global_load_dword v162, v161, s[4:5]
	global_load_dword v163, v161, s[4:5] offset:64
	global_load_dword v164, v161, s[4:5] offset:128
	global_load_dword v165, v161, s[4:5] offset:192
	global_load_dword v166, v161, s[4:5] offset:256
	global_load_dword v167, v161, s[4:5] offset:320
	global_load_dword v168, v161, s[4:5] offset:384
	global_load_dword v169, v161, s[4:5] offset:448
	v_readlane_b32 s4, v252, 60
	v_readlane_b32 s5, v252, 61
	s_nop 4
	global_load_dword v170, v161, s[4:5]
	global_load_dword v171, v161, s[4:5] offset:64
	global_load_dword v172, v161, s[4:5] offset:128
	global_load_dword v173, v161, s[4:5] offset:192
	global_load_dword v174, v161, s[4:5] offset:256
	global_load_dword v175, v161, s[4:5] offset:320
	global_load_dword v176, v161, s[4:5] offset:384
	global_load_dword v177, v161, s[4:5] offset:448
	s_waitcnt vmcnt(32)
	v_readlane_b32 s4, v252, 58
	v_lshlrev_b32_e32 v61, 2, v61
	v_readlane_b32 s5, v252, 59
	s_nop 4
	v_mov_b32_e32 v64, v144
	v_readlane_b32 s4, v252, 60
	v_readlane_b32 s5, v252, 61
	s_nop 4
	v_mov_b32_e32 v61, v152
	v_mul_f32_e32 v62, v54, v61
	v_mul_f32_e32 v61, v6, v61
	v_fma_f32 v62, v6, v64, -v62
	v_fmac_f32_e32 v61, v54, v64
	v_cvt_pk_bf16_f32 v65, v62, s0
	v_lshl_add_u64 v[62:63], v[132:133], 1, v[58:59]
	v_cvt_pk_bf16_f32 v61, v61, s0
	global_store_short v[62:63], v65, off
	global_store_short v[62:63], v61, off offset:64
	s_and_saveexec_b64 s[4:5], s[10:11]
	s_cbranch_execz .LBB0_2176
	v_cvt_pk_bf16_f32 v61, v6, s0
	v_lshl_add_u64 v[62:63], v[134:135], 1, v[58:59]
	v_cvt_pk_bf16_f32 v54, v54, s0
	global_store_short v[62:63], v61, off
	global_store_short v[62:63], v54, off offset:64

; DEV u16 f2bf(float f) { return (u16)(pack2(f, 0.f) & 0xffffu); }
; DEV void phase_win(const Params& P, int l, const u16* __restrict__ xb, const u16* __restrict__ Wt, u16* __restrict__ h, char* smem) {
;     ...
;           int row = m0 + wm * 128 + ms * 16 + quad * 4 + j;
;           int pos = row & (S - 1);
;           u16* hr = h + (size_t)row * HS;
; #pragma unroll
;           for (int ns = 0; ns < 2; ++ns) {
;             int d1 = ns * 16 + l15;
;             float x1 = acc[ms][ns][j], x2 = acc[ms][ns + 2][j];
;             float cs = cosT[pos * 32 + d1], sn = sinT[pos * 32 + d1];
;             hr[dst + d1] = f2bf(x1 * cs - x2 * sn);
;             hr[dst + d1 + 32] = f2bf(x1 * sn + x2 * cs);
;             if (cb < 256) {
;               hr[cb + d1] = f2bf(x1);
;               hr[cb + d1 + 32] = f2bf(x2);
;             }
;           }
.LBB0_2190:
	s_or_b64 exec, exec, s[4:5]
	v_add_u32_e32 v0, s16, v239
	v_mov_b64_e32 v[46:47], s[72:73]
	s_movk_i32 s4, 0x1b00
	v_lshlrev_b32_e32 v48, 5, v0
	v_mad_i64_i32 v[46:47], s[4:5], v0, s4, v[46:47]
	v_and_b32_e32 v48, 0x1ff80, v48
	v_or_b32_e32 v49, v48, v186
	s_waitcnt vmcnt(16)
	v_readlane_b32 s4, v252, 58
	v_lshlrev_b32_e32 v49, 2, v49
	v_readlane_b32 s5, v252, 59
	s_nop 4
	v_mov_b32_e32 v52, v162
	v_readlane_b32 s4, v252, 60
	v_readlane_b32 s5, v252, 61
	s_nop 4
	v_mov_b32_e32 v49, v170
	v_mul_f32_e32 v50, v42, v49
	v_mul_f32_e32 v49, v2, v49
	v_fma_f32 v50, v2, v52, -v50
	v_fmac_f32_e32 v49, v42, v52
	v_cvt_pk_bf16_f32 v53, v50, s0
	v_lshl_add_u64 v[50:51], v[132:133], 1, v[46:47]
	v_cvt_pk_bf16_f32 v49, v49, s0
	global_store_short v[50:51], v53, off
	global_store_short v[50:51], v49, off offset:64
	s_and_saveexec_b64 s[4:5], s[10:11]
	s_cbranch_execz .LBB0_2192
	v_cvt_pk_bf16_f32 v49, v2, s0
	v_lshl_add_u64 v[50:51], v[134:135], 1, v[46:47]
	v_cvt_pk_bf16_f32 v42, v42, s0
	global_store_short v[50:51], v49, off
	global_store_short v[50:51], v42, off offset:64
.LBB0_2192:
	s_or_b64 exec, exec, s[4:5]
	v_or_b32_e32 v42, v48, v240
	v_readlane_b32 s4, v252, 58
	v_lshlrev_b32_e32 v42, 2, v42
	v_readlane_b32 s5, v252, 59
	s_nop 4
	v_mov_b32_e32 v50, v163
	v_readlane_b32 s4, v252, 60
	v_readlane_b32 s5, v252, 61
	s_nop 4
	v_mov_b32_e32 v42, v171
	v_mul_f32_e32 v48, v30, v42
	v_mul_f32_e32 v42, v34, v42
	v_fma_f32 v48, v34, v50, -v48
	v_fmac_f32_e32 v42, v30, v50
	v_cvt_pk_bf16_f32 v51, v48, s0
	v_lshl_add_u64 v[48:49], v[136:137], 1, v[46:47]
	v_cvt_pk_bf16_f32 v42, v42, s0
	global_store_short v[48:49], v51, off offset:32
	global_store_short v[48:49], v42, off offset:96
	s_and_saveexec_b64 s[4:5], s[10:11]
	s_cbranch_execz .LBB0_2194
	v_lshl_add_u64 v[48:49], v[130:131], 0, v[186:187]
	v_cvt_pk_bf16_f32 v34, v34, s0
	v_lshl_add_u64 v[46:47], v[48:49], 1, v[46:47]
	v_cvt_pk_bf16_f32 v30, v30, s0
	global_store_short v[46:47], v34, off offset:32
	global_store_short v[46:47], v30, off offset:96
.LBB0_2194:
	s_or_b64 exec, exec, s[4:5]
	v_or_b32_e32 v30, 1, v0
	v_mov_b64_e32 v[46:47], s[72:73]
	s_movk_i32 s4, 0x1b00
	v_mad_i64_i32 v[46:47], s[4:5], v30, s4, v[46:47]
	v_lshlrev_b32_e32 v30, 5, v30
	v_and_b32_e32 v30, 0x1ffe0, v30
	v_or_b32_e32 v34, v30, v186
	v_readlane_b32 s4, v252, 58
	v_lshlrev_b32_e32 v34, 2, v34
	v_readlane_b32 s5, v252, 59
	s_nop 4
	v_mov_b32_e32 v42, v164
	v_readlane_b32 s4, v252, 60
	v_readlane_b32 s5, v252, 61
	s_nop 4
	v_mov_b32_e32 v34, v172
	v_mul_f32_e32 v48, v43, v34
	v_mul_f32_e32 v34, v3, v34
	v_fma_f32 v48, v3, v42, -v48
	v_fmac_f32_e32 v34, v43, v42
	v_cvt_pk_bf16_f32 v50, v48, s0
	v_lshl_add_u64 v[48:49], v[132:133], 1, v[46:47]
	v_cvt_pk_bf16_f32 v34, v34, s0
	global_store_short v[48:49], v50, off
	global_store_short v[48:49], v34, off offset:64
	s_and_saveexec_b64 s[4:5], s[10:11]
	s_cbranch_execz .LBB0_2196
	v_cvt_pk_bf16_f32 v34, v3, s0
	v_cvt_pk_bf16_f32 v48, v43, s0
	v_lshl_add_u64 v[42:43], v[134:135], 1, v[46:47]
	global_store_short v[42:43], v34, off
	global_store_short v[42:43], v48, off offset:64
.LBB0_2196:
	s_or_b64 exec, exec, s[4:5]
	v_or_b32_e32 v30, v30, v240
	v_readlane_b32 s4, v252, 58
	v_lshlrev_b32_e32 v30, 2, v30
	v_readlane_b32 s5, v252, 59
	s_nop 4
	v_mov_b32_e32 v34, v165
	v_readlane_b32 s4, v252, 60
	v_readlane_b32 s5, v252, 61
	s_nop 4
	v_mov_b32_e32 v30, v173
	v_mul_f32_e32 v42, v31, v30
	v_mul_f32_e32 v30, v35, v30
	v_fma_f32 v42, v35, v34, -v42
	v_fmac_f32_e32 v30, v31, v34
	v_cvt_pk_bf16_f32 v48, v42, s0
	v_lshl_add_u64 v[42:43], v[136:137], 1, v[46:47]
	v_cvt_pk_bf16_f32 v30, v30, s0
	global_store_short v[42:43], v48, off offset:32
	global_store_short v[42:43], v30, off offset:96
	s_and_saveexec_b64 s[4:5], s[10:11]
	s_cbranch_execz .LBB0_2198
	v_cvt_pk_bf16_f32 v34, v35, s0
	v_cvt_pk_bf16_f32 v35, v31, s0
	v_lshl_add_u64 v[30:31], v[130:131], 0, v[186:187]
	v_lshl_add_u64 v[30:31], v[30:31], 1, v[46:47]
	global_store_short v[30:31], v34, off offset:32
	global_store_short v[30:31], v35, off offset:96
; DEV u16 f2bf(float f) { return (u16)(pack2(f, 0.f) & 0xffffu); }
; DEV void phase_win(const Params& P, int l, const u16* __restrict__ xb, const u16* __restrict__ Wt, u16* __restrict__ h, char* smem) {
;     ...
;           int row = m0 + wm * 128 + ms * 16 + quad * 4 + j;
;           int pos = row & (S - 1);
;           u16* hr = h + (size_t)row * HS;
; #pragma unroll
;           for (int ns = 0; ns < 2; ++ns) {
;             int d1 = ns * 16 + l15;
;             float x1 = acc[ms][ns][j], x2 = acc[ms][ns + 2][j];
;             float cs = cosT[pos * 32 + d1], sn = sinT[pos * 32 + d1];
;             hr[dst + d1] = f2bf(x1 * cs - x2 * sn);
;             hr[dst + d1 + 32] = f2bf(x1 * sn + x2 * cs);
;             if (cb < 256) {
;               hr[cb + d1] = f2bf(x1);
;               hr[cb + d1 + 32] = f2bf(x2);
;             }
;           }
.LBB0_2198:
	s_or_b64 exec, exec, s[4:5]
	v_or_b32_e32 v34, 2, v0
	v_mov_b64_e32 v[30:31], s[72:73]
	s_movk_i32 s4, 0x1b00
	v_mad_i64_i32 v[30:31], s[4:5], v34, s4, v[30:31]
	v_lshlrev_b32_e32 v34, 5, v34
	v_and_b32_e32 v34, 0x1ffe0, v34
	v_or_b32_e32 v35, v34, v186
	v_readlane_b32 s4, v252, 58
	v_lshlrev_b32_e32 v35, 2, v35
	v_readlane_b32 s5, v252, 59
	s_nop 4
	v_mov_b32_e32 v46, v166
	v_readlane_b32 s4, v252, 60
	v_readlane_b32 s5, v252, 61
	s_nop 4
	v_mov_b32_e32 v35, v174
	v_mul_f32_e32 v42, v44, v35
	v_mul_f32_e32 v35, v4, v35
	v_fma_f32 v42, v4, v46, -v42
	v_fmac_f32_e32 v35, v44, v46
	v_cvt_pk_bf16_f32 v47, v42, s0
	v_lshl_add_u64 v[42:43], v[132:133], 1, v[30:31]
	v_cvt_pk_bf16_f32 v35, v35, s0
	global_store_short v[42:43], v47, off
	global_store_short v[42:43], v35, off offset:64
	s_and_saveexec_b64 s[4:5], s[10:11]
	s_cbranch_execz .LBB0_2200
	v_cvt_pk_bf16_f32 v35, v4, s0
	v_lshl_add_u64 v[42:43], v[134:135], 1, v[30:31]
	v_cvt_pk_bf16_f32 v44, v44, s0
	global_store_short v[42:43], v35, off
	global_store_short v[42:43], v44, off offset:64
.LBB0_2200:
	s_or_b64 exec, exec, s[4:5]
	v_or_b32_e32 v34, v34, v240
	v_readlane_b32 s4, v252, 58
	v_lshlrev_b32_e32 v34, 2, v34
	v_readlane_b32 s5, v252, 59
	s_nop 4
	v_mov_b32_e32 v42, v167
	v_readlane_b32 s4, v252, 60
	v_readlane_b32 s5, v252, 61
	s_nop 4
	v_mov_b32_e32 v43, v175
	v_mul_f32_e32 v34, v32, v43
	v_mul_f32_e32 v43, v36, v43
	v_fma_f32 v34, v36, v42, -v34
	v_fmac_f32_e32 v43, v32, v42
	v_cvt_pk_bf16_f32 v44, v34, s0
	v_lshl_add_u64 v[34:35], v[136:137], 1, v[30:31]
	v_cvt_pk_bf16_f32 v42, v43, s0
	global_store_short v[34:35], v44, off offset:32
	global_store_short v[34:35], v42, off offset:96
	s_and_saveexec_b64 s[4:5], s[10:11]
	s_cbranch_execz .LBB0_2202
	v_lshl_add_u64 v[34:35], v[130:131], 0, v[186:187]
	v_cvt_pk_bf16_f32 v36, v36, s0
	v_lshl_add_u64 v[30:31], v[34:35], 1, v[30:31]
	v_cvt_pk_bf16_f32 v32, v32, s0
	global_store_short v[30:31], v36, off offset:32
	global_store_short v[30:31], v32, off offset:96
.LBB0_2202:
	s_or_b64 exec, exec, s[4:5]
	v_or_b32_e32 v32, 3, v0
	v_lshlrev_b32_e32 v0, 5, v32
	v_and_b32_e32 v0, 0x1ffe0, v0
	v_or_b32_e32 v30, v0, v186
	v_readlane_b32 s4, v252, 60
	v_lshlrev_b32_e32 v30, 2, v30
	v_readlane_b32 s5, v252, 61
	s_nop 4
	v_mov_b32_e32 v36, v176
	v_readlane_b32 s4, v252, 58
	v_readlane_b32 s5, v252, 59
	s_nop 4
	v_mov_b32_e32 v42, v168
	v_mov_b64_e32 v[30:31], s[72:73]
	s_movk_i32 s4, 0x1b00
	v_mad_i64_i32 v[30:31], s[4:5], v32, s4, v[30:31]
	v_lshl_add_u64 v[34:35], v[132:133], 1, v[30:31]
	v_mul_f32_e32 v32, v45, v36
	v_mul_f32_e32 v36, v5, v36
	v_fma_f32 v32, v5, v42, -v32
	v_fmac_f32_e32 v36, v45, v42
	v_cvt_pk_bf16_f32 v32, v32, s0
	v_cvt_pk_bf16_f32 v36, v36, s0
	global_store_short v[34:35], v32, off
	global_store_short v[34:35], v36, off offset:64
	s_and_saveexec_b64 s[4:5], s[10:11]
	s_cbranch_execz .LBB0_2204
	v_cvt_pk_bf16_f32 v32, v5, s0
	v_lshl_add_u64 v[34:35], v[134:135], 1, v[30:31]
	v_cvt_pk_bf16_f32 v36, v45, s0
	global_store_short v[34:35], v32, off
	global_store_short v[34:35], v36, off offset:64
.LBB0_2204:
	s_or_b64 exec, exec, s[4:5]
	v_or_b32_e32 v0, v0, v240
	v_readlane_b32 s4, v252, 60
	v_lshlrev_b32_e32 v0, 2, v0
	v_readlane_b32 s5, v252, 61
	v_lshl_add_u64 v[34:35], v[136:137], 1, v[30:31]
	s_nop 3
	v_mov_b32_e32 v32, v177
	v_readlane_b32 s4, v252, 58
	v_readlane_b32 s5, v252, 59
	v_mul_f32_e32 v36, v33, v32
	s_nop 2
	v_mov_b32_e32 v0, v169
	v_mul_f32_e32 v32, v37, v32
	v_fma_f32 v36, v37, v0, -v36
	v_fmac_f32_e32 v32, v33, v0
	v_cvt_pk_bf16_f32 v0, v36, s0
	v_cvt_pk_bf16_f32 v32, v32, s0
	global_store_short v[34:35], v0, off offset:32
	global_store_short v[34:35], v32, off offset:96
	s_and_b64 exec, exec, s[10:11]
	s_cbranch_execz .LBB0_2206
	v_cvt_pk_bf16_f32 v34, v33, s0
	v_lshl_add_u64 v[32:33], v[130:131], 0, v[186:187]
	v_cvt_pk_bf16_f32 v0, v37, s0
	v_lshl_add_u64 v[30:31], v[32:33], 1, v[30:31]
	global_store_short v[30:31], v0, off offset:32
	global_store_short v[30:31], v34, off offset:96
